# filter-stage-4 items moved from bandwidth-bound phase 1 into the idle window of the 192 non-chain workgroups at the end of phase 4
# speedup vs baseline: 1.0257x; 1.0177x over previous
.LBB0_220:
	s_sub_i32 s2, s34, 32
	s_and_b64 s[0:1], s[0:1], exec
	s_cselect_b32 s25, s2, s34
	s_cmpk_gt_i32 s24, 0xff
	s_cbranch_scc1 .LBB0_227
	s_cmp_lg_u32 s34, 0x100
	s_cbranch_scc1 .Lp1_filt4_entry
	s_branch .LBB0_227

.LBB0_227:
	s_cmp_eq_u32 s100, 3
	s_cbranch_scc1 .LBB0_845
	s_cmp_eq_u32 s100, 2
	s_cbranch_scc1 .LBB0_281
	s_add_u32 s2, s22, 0x30bc000
	s_addc_u32 s3, s23, 0
	s_lshl_b32 s29, s25, 3
	s_abs_i32 s28, s29
	v_cvt_f32_u32_e32 v0, s28
	s_add_i32 s0, s29, 0x7fff
	s_sub_i32 s10, 0xffff8001, s29
	s_ashr_i32 s1, s0, 31
	v_rcp_iflag_f32_e32 v0, v0
	s_max_i32 s0, s0, s10
	s_sub_i32 s10, 0, s28
	s_ashr_i32 s30, s29, 31
	v_mul_f32_e32 v0, 0x4f7ffffe, v0
	v_cvt_u32_f32_e32 v0, v0
	s_xor_b32 s1, s1, s30
	v_lshrrev_b32_e32 v1, 6, v160
	v_lshl_add_u32 v99, s24, 3, v1
	v_readfirstlane_b32 s31, v0
	s_mul_i32 s10, s10, s31
	s_mul_hi_u32 s10, s31, s10
	s_add_i32 s31, s31, s10
	s_mul_hi_u32 s10, s0, s31
	s_mul_i32 s11, s10, s28
	s_sub_i32 s0, s0, s11
	s_add_i32 s11, s10, 1
	s_sub_i32 s12, s0, s28
	s_cmp_ge_u32 s0, s28
	s_cselect_b32 s10, s11, s10
	s_cselect_b32 s0, s12, s0
	s_add_i32 s11, s10, 1
	s_cmp_ge_u32 s0, s28
	s_cselect_b32 s0, s11, s10
	s_xor_b32 s0, s0, s1
	s_sub_i32 s0, s0, s1
	v_mul_lo_u32 v48, s0, v99
	v_add_u32_e32 v0, s0, v48
	v_min_i32_e32 v103, 0x8000, v0
	v_cmp_lt_i32_e32 vcc, v48, v103
	s_and_saveexec_b64 s[10:11], vcc
	s_cbranch_execz .LBB0_256
	v_ashrrev_i32_e32 v49, 31, v48
	v_readlane_b32 s36, v240, 8
	v_lshlrev_b32_e32 v2, 2, v160
	v_lshlrev_b64 v[0:1], 12, v[48:49]
	v_readlane_b32 s37, v240, 9
	v_and_b32_e32 v52, 0xfc, v2
	v_mov_b32_e32 v97, 0
	v_lshl_add_u64 v[0:1], s[36:37], 0, v[0:1]
	v_lshlrev_b32_e32 v96, 2, v52
	v_lshl_add_u64 v[12:13], v[0:1], 0, v[96:97]
	global_load_dwordx4 v[0:3], v[12:13], off nt
	global_load_dwordx4 v[4:7], v[12:13], off offset:1024 nt
	global_load_dwordx4 v[8:11], v[12:13], off offset:2048 nt
	s_nop 0
	global_load_dwordx4 v[12:15], v[12:13], off offset:3072 nt
	v_add_u32_e32 v32, 1, v48
	v_cmp_lt_i32_e32 vcc, v32, v103
	v_readlane_b32 s38, v240, 10
	v_readlane_b32 s39, v240, 11
	v_readlane_b32 s40, v240, 12
	v_readlane_b32 s41, v240, 13
	v_readlane_b32 s42, v240, 14
	v_readlane_b32 s43, v240, 15
	v_readlane_b32 s44, v240, 16
	v_readlane_b32 s45, v240, 17
	v_readlane_b32 s46, v240, 18
	v_readlane_b32 s47, v240, 19
	v_readlane_b32 s48, v240, 20
	v_readlane_b32 s49, v240, 21
	v_readlane_b32 s50, v240, 22
	v_readlane_b32 s51, v240, 23
	s_and_saveexec_b64 s[0:1], vcc
	s_cbranch_execz .LBB0_230
	v_ashrrev_i32_e32 v33, 31, v32
	v_readlane_b32 s36, v240, 8
	s_waitcnt vmcnt(12)
	v_lshlrev_b64 v[16:17], 12, v[32:33]
	v_readlane_b32 s37, v240, 9
	v_readlane_b32 s38, v240, 10
	v_readlane_b32 s39, v240, 11
	v_lshl_add_u64 v[16:17], s[36:37], 0, v[16:17]
	v_lshl_add_u64 v[28:29], v[16:17], 0, v[96:97]
	global_load_dwordx4 v[16:19], v[28:29], off nt
	global_load_dwordx4 v[20:23], v[28:29], off offset:1024 nt
	global_load_dwordx4 v[24:27], v[28:29], off offset:2048 nt
	s_nop 0
	global_load_dwordx4 v[28:31], v[28:29], off offset:3072 nt
	v_readlane_b32 s40, v240, 12
	v_readlane_b32 s41, v240, 13
	v_readlane_b32 s42, v240, 14
	v_readlane_b32 s43, v240, 15
	v_readlane_b32 s44, v240, 16
	v_readlane_b32 s45, v240, 17
	v_readlane_b32 s46, v240, 18
	v_readlane_b32 s47, v240, 19
	v_readlane_b32 s48, v240, 20
	v_readlane_b32 s49, v240, 21
	v_readlane_b32 s50, v240, 22
	v_readlane_b32 s51, v240, 23

.LBB0_844:
	s_waitcnt lgkmcnt(0)
	s_barrier
	s_cmp_lg_u32 s34, 0x100
	s_cbranch_scc1 .LBB0_845
	s_mov_b32 s100, 3
	s_sub_i32 s24, s20, 64
	s_movk_i32 s25, 0xc0
	s_branch .Lp1_filt4_entry

.LBB0_937:
	s_bitcmp1_b32 s57, 0
	s_cselect_b32 s26, 0x10400, 0
	s_add_i32 s26, s26, 0
	s_mov_b64 s[30:31], -1
	s_andn2_b64 vcc, exec, s[28:29]
	v_add_u32_e32 v1, s26, v196
	s_cbranch_vccnz .LBB0_941
	s_lshl_b32 s26, s57, 9
	s_mov_b32 s30, 0
	s_mov_b64 s[28:29], -1
	s_lshl_b32 s26, s26, 1
	v_add_u32_e32 v15, s26, v201
	ds_read_b128 v[2:5], v1 offset:16640
	ds_read_b128 v[10:13], v15 offset:8192
	ds_read_b128 v[216:219], v1 offset:49920
	ds_read_b128 v[224:227], v15 offset:7680
	ds_read_b128 v[6:9], v1 offset:16672
	ds_read_b128 v[212:215], v15 offset:8224
	ds_read_b128 v[220:223], v1 offset:49952
	ds_read_b128 v[228:231], v15 offset:7712
	ds_read_b128 v[244:247], v1 offset:16704
	ds_read_b128 v[232:235], v15 offset:8256
	ds_read_b128 v[248:251], v1 offset:49984
	ds_read_b128 v[236:239], v15 offset:7744
	s_waitcnt lgkmcnt(8)
	v_mfma_f32_32x32x16_bf16 v[64:79], v[10:13], v[2:5], v[64:79]
	v_mfma_f32_32x32x16_bf16 v[48:63], v[10:13], v[216:219], v[48:63]
	v_mfma_f32_32x32x16_bf16 v[32:47], v[224:227], v[2:5], v[32:47]
	v_mfma_f32_32x32x16_bf16 v[16:31], v[224:227], v[216:219], v[16:31]
	ds_read_b128 v[2:5], v1 offset:16736
	ds_read_b128 v[10:13], v15 offset:8288
	ds_read_b128 v[216:219], v1 offset:50016
	ds_read_b128 v[224:227], v15 offset:7776
	s_waitcnt lgkmcnt(8)
	v_mfma_f32_32x32x16_bf16 v[64:79], v[212:215], v[6:9], v[64:79]
	v_mfma_f32_32x32x16_bf16 v[48:63], v[212:215], v[220:223], v[48:63]
	v_mfma_f32_32x32x16_bf16 v[32:47], v[228:231], v[6:9], v[32:47]
	v_mfma_f32_32x32x16_bf16 v[16:31], v[228:231], v[220:223], v[16:31]
	ds_read_b128 v[6:9], v1 offset:16768
	ds_read_b128 v[212:215], v15 offset:8320
	ds_read_b128 v[220:223], v1 offset:50048
	ds_read_b128 v[228:231], v15 offset:7808
	s_waitcnt lgkmcnt(8)
	v_mfma_f32_32x32x16_bf16 v[64:79], v[232:235], v[244:247], v[64:79]
	v_mfma_f32_32x32x16_bf16 v[48:63], v[232:235], v[248:251], v[48:63]
	v_mfma_f32_32x32x16_bf16 v[32:47], v[236:239], v[244:247], v[32:47]
	v_mfma_f32_32x32x16_bf16 v[16:31], v[236:239], v[248:251], v[16:31]
	ds_read_b128 v[244:247], v1 offset:16800
	ds_read_b128 v[232:235], v15 offset:8352
	ds_read_b128 v[248:251], v1 offset:50080
	ds_read_b128 v[236:239], v15 offset:7840
	s_waitcnt lgkmcnt(8)
	v_mfma_f32_32x32x16_bf16 v[64:79], v[10:13], v[2:5], v[64:79]
	v_mfma_f32_32x32x16_bf16 v[48:63], v[10:13], v[216:219], v[48:63]
	v_mfma_f32_32x32x16_bf16 v[32:47], v[224:227], v[2:5], v[32:47]
	v_mfma_f32_32x32x16_bf16 v[16:31], v[224:227], v[216:219], v[16:31]
	ds_read_b128 v[2:5], v1 offset:16832
	ds_read_b128 v[10:13], v15 offset:8384
	ds_read_b128 v[216:219], v1 offset:50112
	ds_read_b128 v[224:227], v15 offset:7872
	s_waitcnt lgkmcnt(8)
	v_mfma_f32_32x32x16_bf16 v[64:79], v[212:215], v[6:9], v[64:79]
	v_mfma_f32_32x32x16_bf16 v[48:63], v[212:215], v[220:223], v[48:63]
	v_mfma_f32_32x32x16_bf16 v[32:47], v[228:231], v[6:9], v[32:47]
	v_mfma_f32_32x32x16_bf16 v[16:31], v[228:231], v[220:223], v[16:31]
	ds_read_b128 v[6:9], v1 offset:16864
	ds_read_b128 v[212:215], v15 offset:8416
	ds_read_b128 v[220:223], v1 offset:50144
	ds_read_b128 v[228:231], v15 offset:7904
	s_waitcnt lgkmcnt(8)
	v_mfma_f32_32x32x16_bf16 v[64:79], v[232:235], v[244:247], v[64:79]
	v_mfma_f32_32x32x16_bf16 v[48:63], v[232:235], v[248:251], v[48:63]
	v_mfma_f32_32x32x16_bf16 v[32:47], v[236:239], v[244:247], v[32:47]
	v_mfma_f32_32x32x16_bf16 v[16:31], v[236:239], v[248:251], v[16:31]
	ds_read_b128 v[244:247], v1 offset:16896
	ds_read_b128 v[232:235], v15 offset:8448
	ds_read_b128 v[248:251], v1 offset:50176
	ds_read_b128 v[236:239], v15 offset:7936
	s_waitcnt lgkmcnt(8)
	v_mfma_f32_32x32x16_bf16 v[64:79], v[10:13], v[2:5], v[64:79]
	v_mfma_f32_32x32x16_bf16 v[48:63], v[10:13], v[216:219], v[48:63]
	v_mfma_f32_32x32x16_bf16 v[32:47], v[224:227], v[2:5], v[32:47]
	v_mfma_f32_32x32x16_bf16 v[16:31], v[224:227], v[216:219], v[16:31]
	ds_read_b128 v[2:5], v1 offset:16928
	ds_read_b128 v[10:13], v15 offset:8480
	ds_read_b128 v[216:219], v1 offset:50208
	ds_read_b128 v[224:227], v15 offset:7968
	s_waitcnt lgkmcnt(8)
	v_mfma_f32_32x32x16_bf16 v[64:79], v[212:215], v[6:9], v[64:79]
	v_mfma_f32_32x32x16_bf16 v[48:63], v[212:215], v[220:223], v[48:63]
	v_mfma_f32_32x32x16_bf16 v[32:47], v[228:231], v[6:9], v[32:47]
	v_mfma_f32_32x32x16_bf16 v[16:31], v[228:231], v[220:223], v[16:31]
	ds_read_b128 v[6:9], v1 offset:16960
	ds_read_b128 v[212:215], v15 offset:8512
	ds_read_b128 v[220:223], v1 offset:50240
	ds_read_b128 v[228:231], v15 offset:8000
	s_waitcnt lgkmcnt(8)
	v_mfma_f32_32x32x16_bf16 v[64:79], v[232:235], v[244:247], v[64:79]
	v_mfma_f32_32x32x16_bf16 v[48:63], v[232:235], v[248:251], v[48:63]
	v_mfma_f32_32x32x16_bf16 v[32:47], v[236:239], v[244:247], v[32:47]
	v_mfma_f32_32x32x16_bf16 v[16:31], v[236:239], v[248:251], v[16:31]
	ds_read_b128 v[244:247], v1 offset:16992
	ds_read_b128 v[232:235], v15 offset:8544
	ds_read_b128 v[248:251], v1 offset:50272
	ds_read_b128 v[236:239], v15 offset:8032
	s_waitcnt lgkmcnt(8)
	v_mfma_f32_32x32x16_bf16 v[64:79], v[10:13], v[2:5], v[64:79]
	v_mfma_f32_32x32x16_bf16 v[48:63], v[10:13], v[216:219], v[48:63]
	v_mfma_f32_32x32x16_bf16 v[32:47], v[224:227], v[2:5], v[32:47]
	v_mfma_f32_32x32x16_bf16 v[16:31], v[224:227], v[216:219], v[16:31]
	ds_read_b128 v[2:5], v1 offset:17024
	ds_read_b128 v[10:13], v15 offset:8576
	ds_read_b128 v[216:219], v1 offset:50304
	ds_read_b128 v[224:227], v15 offset:8064
	s_waitcnt lgkmcnt(8)
	v_mfma_f32_32x32x16_bf16 v[64:79], v[212:215], v[6:9], v[64:79]
	v_mfma_f32_32x32x16_bf16 v[48:63], v[212:215], v[220:223], v[48:63]
	v_mfma_f32_32x32x16_bf16 v[32:47], v[228:231], v[6:9], v[32:47]
	v_mfma_f32_32x32x16_bf16 v[16:31], v[228:231], v[220:223], v[16:31]
	ds_read_b128 v[6:9], v1 offset:17056
	ds_read_b128 v[212:215], v15 offset:8608
	ds_read_b128 v[220:223], v1 offset:50336
	ds_read_b128 v[228:231], v15 offset:8096
	s_waitcnt lgkmcnt(8)
	v_mfma_f32_32x32x16_bf16 v[64:79], v[232:235], v[244:247], v[64:79]
	v_mfma_f32_32x32x16_bf16 v[48:63], v[232:235], v[248:251], v[48:63]
	v_mfma_f32_32x32x16_bf16 v[32:47], v[236:239], v[244:247], v[32:47]
	v_mfma_f32_32x32x16_bf16 v[16:31], v[236:239], v[248:251], v[16:31]
	ds_read_b128 v[244:247], v1 offset:17088
	ds_read_b128 v[232:235], v15 offset:8640
	ds_read_b128 v[248:251], v1 offset:50368
	ds_read_b128 v[236:239], v15 offset:8128
	s_waitcnt lgkmcnt(8)
	v_mfma_f32_32x32x16_bf16 v[64:79], v[10:13], v[2:5], v[64:79]
	v_mfma_f32_32x32x16_bf16 v[48:63], v[10:13], v[216:219], v[48:63]
	v_mfma_f32_32x32x16_bf16 v[32:47], v[224:227], v[2:5], v[32:47]
	v_mfma_f32_32x32x16_bf16 v[16:31], v[224:227], v[216:219], v[16:31]
	ds_read_b128 v[2:5], v1 offset:17120
	ds_read_b128 v[10:13], v15 offset:8672
	ds_read_b128 v[216:219], v1 offset:50400
	ds_read_b128 v[224:227], v15 offset:8160
	s_waitcnt lgkmcnt(8)
	v_mfma_f32_32x32x16_bf16 v[64:79], v[212:215], v[6:9], v[64:79]
	v_mfma_f32_32x32x16_bf16 v[48:63], v[212:215], v[220:223], v[48:63]
	v_mfma_f32_32x32x16_bf16 v[32:47], v[228:231], v[6:9], v[32:47]
	v_mfma_f32_32x32x16_bf16 v[16:31], v[228:231], v[220:223], v[16:31]
	ds_read_b128 v[6:9], v1 offset:17152
	ds_read_b128 v[212:215], v15 offset:8704
	ds_read_b128 v[220:223], v1 offset:50432
	ds_read_b128 v[228:231], v15 offset:8192
	s_waitcnt lgkmcnt(8)
	v_mfma_f32_32x32x16_bf16 v[64:79], v[232:235], v[244:247], v[64:79]
	v_mfma_f32_32x32x16_bf16 v[48:63], v[232:235], v[248:251], v[48:63]
	v_mfma_f32_32x32x16_bf16 v[32:47], v[236:239], v[244:247], v[32:47]
	v_mfma_f32_32x32x16_bf16 v[16:31], v[236:239], v[248:251], v[16:31]
	ds_read_b128 v[244:247], v1 offset:17184
	ds_read_b128 v[232:235], v15 offset:8736
	ds_read_b128 v[248:251], v1 offset:50464
	ds_read_b128 v[236:239], v15 offset:8224
	s_waitcnt lgkmcnt(8)
	v_mfma_f32_32x32x16_bf16 v[64:79], v[10:13], v[2:5], v[64:79]
	v_mfma_f32_32x32x16_bf16 v[48:63], v[10:13], v[216:219], v[48:63]
	v_mfma_f32_32x32x16_bf16 v[32:47], v[224:227], v[2:5], v[32:47]
	v_mfma_f32_32x32x16_bf16 v[16:31], v[224:227], v[216:219], v[16:31]
	ds_read_b128 v[2:5], v1 offset:17216
	ds_read_b128 v[10:13], v15 offset:8768
	ds_read_b128 v[216:219], v1 offset:50496
	ds_read_b128 v[224:227], v15 offset:8256
	s_waitcnt lgkmcnt(8)
	v_mfma_f32_32x32x16_bf16 v[64:79], v[212:215], v[6:9], v[64:79]
	v_mfma_f32_32x32x16_bf16 v[48:63], v[212:215], v[220:223], v[48:63]
	v_mfma_f32_32x32x16_bf16 v[32:47], v[228:231], v[6:9], v[32:47]
	v_mfma_f32_32x32x16_bf16 v[16:31], v[228:231], v[220:223], v[16:31]
	ds_read_b128 v[6:9], v1 offset:17248
	ds_read_b128 v[212:215], v15 offset:8800
	ds_read_b128 v[220:223], v1 offset:50528
	ds_read_b128 v[228:231], v15 offset:8288
	s_waitcnt lgkmcnt(8)
	v_mfma_f32_32x32x16_bf16 v[64:79], v[232:235], v[244:247], v[64:79]
	v_mfma_f32_32x32x16_bf16 v[48:63], v[232:235], v[248:251], v[48:63]
	v_mfma_f32_32x32x16_bf16 v[32:47], v[236:239], v[244:247], v[32:47]
	v_mfma_f32_32x32x16_bf16 v[16:31], v[236:239], v[248:251], v[16:31]
	ds_read_b128 v[244:247], v1 offset:17280
	ds_read_b128 v[232:235], v15 offset:8832
	ds_read_b128 v[248:251], v1 offset:50560
	ds_read_b128 v[236:239], v15 offset:8320
	s_waitcnt lgkmcnt(8)
	v_mfma_f32_32x32x16_bf16 v[64:79], v[10:13], v[2:5], v[64:79]
	v_mfma_f32_32x32x16_bf16 v[48:63], v[10:13], v[216:219], v[48:63]
	v_mfma_f32_32x32x16_bf16 v[32:47], v[224:227], v[2:5], v[32:47]
	v_mfma_f32_32x32x16_bf16 v[16:31], v[224:227], v[216:219], v[16:31]
	ds_read_b128 v[2:5], v1 offset:17312
	ds_read_b128 v[10:13], v15 offset:8864
	ds_read_b128 v[216:219], v1 offset:50592
	ds_read_b128 v[224:227], v15 offset:8352
	s_waitcnt lgkmcnt(8)
	v_mfma_f32_32x32x16_bf16 v[64:79], v[212:215], v[6:9], v[64:79]
	v_mfma_f32_32x32x16_bf16 v[48:63], v[212:215], v[220:223], v[48:63]
	v_mfma_f32_32x32x16_bf16 v[32:47], v[228:231], v[6:9], v[32:47]
	v_mfma_f32_32x32x16_bf16 v[16:31], v[228:231], v[220:223], v[16:31]
	ds_read_b128 v[6:9], v1 offset:17344
	ds_read_b128 v[212:215], v15 offset:8896
	ds_read_b128 v[220:223], v1 offset:50624
	ds_read_b128 v[228:231], v15 offset:8384
	s_waitcnt lgkmcnt(8)
	v_mfma_f32_32x32x16_bf16 v[64:79], v[232:235], v[244:247], v[64:79]
	v_mfma_f32_32x32x16_bf16 v[48:63], v[232:235], v[248:251], v[48:63]
	v_mfma_f32_32x32x16_bf16 v[32:47], v[236:239], v[244:247], v[32:47]
	v_mfma_f32_32x32x16_bf16 v[16:31], v[236:239], v[248:251], v[16:31]
	ds_read_b128 v[244:247], v1 offset:17376
	ds_read_b128 v[232:235], v15 offset:8928
	ds_read_b128 v[248:251], v1 offset:50656
	ds_read_b128 v[236:239], v15 offset:8416
	s_waitcnt lgkmcnt(8)
	v_mfma_f32_32x32x16_bf16 v[64:79], v[10:13], v[2:5], v[64:79]
	v_mfma_f32_32x32x16_bf16 v[48:63], v[10:13], v[216:219], v[48:63]
	v_mfma_f32_32x32x16_bf16 v[32:47], v[224:227], v[2:5], v[32:47]
	v_mfma_f32_32x32x16_bf16 v[16:31], v[224:227], v[216:219], v[16:31]
	ds_read_b128 v[2:5], v1 offset:17408
	ds_read_b128 v[10:13], v15 offset:8960
	ds_read_b128 v[216:219], v1 offset:50688
	ds_read_b128 v[224:227], v15 offset:8448
	s_waitcnt lgkmcnt(8)
	v_mfma_f32_32x32x16_bf16 v[64:79], v[212:215], v[6:9], v[64:79]
	v_mfma_f32_32x32x16_bf16 v[48:63], v[212:215], v[220:223], v[48:63]
	v_mfma_f32_32x32x16_bf16 v[32:47], v[228:231], v[6:9], v[32:47]
	v_mfma_f32_32x32x16_bf16 v[16:31], v[228:231], v[220:223], v[16:31]
	ds_read_b128 v[6:9], v1 offset:17440
	ds_read_b128 v[212:215], v15 offset:8992
	ds_read_b128 v[220:223], v1 offset:50720
	ds_read_b128 v[228:231], v15 offset:8480
	s_waitcnt lgkmcnt(8)
	v_mfma_f32_32x32x16_bf16 v[64:79], v[232:235], v[244:247], v[64:79]
	v_mfma_f32_32x32x16_bf16 v[48:63], v[232:235], v[248:251], v[48:63]
	v_mfma_f32_32x32x16_bf16 v[32:47], v[236:239], v[244:247], v[32:47]
	v_mfma_f32_32x32x16_bf16 v[16:31], v[236:239], v[248:251], v[16:31]
	ds_read_b128 v[244:247], v1 offset:17472
	ds_read_b128 v[232:235], v15 offset:9024
	ds_read_b128 v[248:251], v1 offset:50752
	ds_read_b128 v[236:239], v15 offset:8512
	s_waitcnt lgkmcnt(8)
	v_mfma_f32_32x32x16_bf16 v[64:79], v[10:13], v[2:5], v[64:79]
	v_mfma_f32_32x32x16_bf16 v[48:63], v[10:13], v[216:219], v[48:63]
	v_mfma_f32_32x32x16_bf16 v[32:47], v[224:227], v[2:5], v[32:47]
	v_mfma_f32_32x32x16_bf16 v[16:31], v[224:227], v[216:219], v[16:31]
	ds_read_b128 v[2:5], v1 offset:17504
	ds_read_b128 v[10:13], v15 offset:9056
	ds_read_b128 v[216:219], v1 offset:50784
	ds_read_b128 v[224:227], v15 offset:8544
	s_waitcnt lgkmcnt(8)
	v_mfma_f32_32x32x16_bf16 v[64:79], v[212:215], v[6:9], v[64:79]
	v_mfma_f32_32x32x16_bf16 v[48:63], v[212:215], v[220:223], v[48:63]
	v_mfma_f32_32x32x16_bf16 v[32:47], v[228:231], v[6:9], v[32:47]
	v_mfma_f32_32x32x16_bf16 v[16:31], v[228:231], v[220:223], v[16:31]
	ds_read_b128 v[6:9], v1 offset:17536
	ds_read_b128 v[212:215], v15 offset:9088
	ds_read_b128 v[220:223], v1 offset:50816
	ds_read_b128 v[228:231], v15 offset:8576
	s_waitcnt lgkmcnt(8)
	v_mfma_f32_32x32x16_bf16 v[64:79], v[232:235], v[244:247], v[64:79]
	v_mfma_f32_32x32x16_bf16 v[48:63], v[232:235], v[248:251], v[48:63]
	v_mfma_f32_32x32x16_bf16 v[32:47], v[236:239], v[244:247], v[32:47]
	v_mfma_f32_32x32x16_bf16 v[16:31], v[236:239], v[248:251], v[16:31]
	ds_read_b128 v[244:247], v1 offset:17568
	ds_read_b128 v[232:235], v15 offset:9120
	ds_read_b128 v[248:251], v1 offset:50848
	ds_read_b128 v[236:239], v15 offset:8608
	s_waitcnt lgkmcnt(8)
	v_mfma_f32_32x32x16_bf16 v[64:79], v[10:13], v[2:5], v[64:79]
	v_mfma_f32_32x32x16_bf16 v[48:63], v[10:13], v[216:219], v[48:63]
	v_mfma_f32_32x32x16_bf16 v[32:47], v[224:227], v[2:5], v[32:47]
	v_mfma_f32_32x32x16_bf16 v[16:31], v[224:227], v[216:219], v[16:31]
	ds_read_b128 v[2:5], v1 offset:17600
	ds_read_b128 v[10:13], v15 offset:9152
	ds_read_b128 v[216:219], v1 offset:50880
	ds_read_b128 v[224:227], v15 offset:8640
	s_waitcnt lgkmcnt(8)
	v_mfma_f32_32x32x16_bf16 v[64:79], v[212:215], v[6:9], v[64:79]
	v_mfma_f32_32x32x16_bf16 v[48:63], v[212:215], v[220:223], v[48:63]
	v_mfma_f32_32x32x16_bf16 v[32:47], v[228:231], v[6:9], v[32:47]
	v_mfma_f32_32x32x16_bf16 v[16:31], v[228:231], v[220:223], v[16:31]
	ds_read_b128 v[6:9], v1 offset:17632
	ds_read_b128 v[212:215], v15 offset:9184
	ds_read_b128 v[220:223], v1 offset:50912
	ds_read_b128 v[228:231], v15 offset:8672
	s_waitcnt lgkmcnt(8)
	v_mfma_f32_32x32x16_bf16 v[64:79], v[232:235], v[244:247], v[64:79]
	v_mfma_f32_32x32x16_bf16 v[48:63], v[232:235], v[248:251], v[48:63]
	v_mfma_f32_32x32x16_bf16 v[32:47], v[236:239], v[244:247], v[32:47]
	v_mfma_f32_32x32x16_bf16 v[16:31], v[236:239], v[248:251], v[16:31]
	s_waitcnt lgkmcnt(4)
	v_mfma_f32_32x32x16_bf16 v[64:79], v[10:13], v[2:5], v[64:79]
	v_mfma_f32_32x32x16_bf16 v[48:63], v[10:13], v[216:219], v[48:63]
	v_mfma_f32_32x32x16_bf16 v[32:47], v[224:227], v[2:5], v[32:47]
	v_mfma_f32_32x32x16_bf16 v[16:31], v[224:227], v[216:219], v[16:31]
	s_waitcnt lgkmcnt(0)
	v_mfma_f32_32x32x16_bf16 v[64:79], v[212:215], v[6:9], v[64:79]
	v_mfma_f32_32x32x16_bf16 v[48:63], v[212:215], v[220:223], v[48:63]
	v_mfma_f32_32x32x16_bf16 v[32:47], v[228:231], v[6:9], v[32:47]
	v_mfma_f32_32x32x16_bf16 v[16:31], v[228:231], v[220:223], v[16:31]
	s_mov_b64 s[30:31], 0

.LBB0_943:
	s_waitcnt lgkmcnt(0)
	s_barrier
	s_cmp_lg_u32 s39, 9
	s_cbranch_scc0 .LBB0_907
	s_nop 4
	s_mov_b32 s57, s39
	s_branch .LBB0_921
